# stack + hyena park loop: packed sincospif only in trip 0, pi/4 rotation after
# speedup vs baseline: 1.0027x; 1.0007x over previous
.LBB0_1038:
	v_ashrrev_i32_e32 v3, 31, v13
	v_mov_b32_e32 v2, v13
	v_ashrrev_i32_e32 v5, 31, v12
	v_mov_b32_e32 v4, v12
	v_lshlrev_b64 v[18:19], 3, v[4:5]
	v_lshlrev_b64 v[22:23], 3, v[2:3]
	ds_read_b128 v[2:5], v35
	ds_read_b128 v[6:9], v35 offset:16
	ds_read_b128 v[14:17], v35 offset:16384
	v_lshl_add_u64 v[20:21], s[84:85], 0, v[18:19]
	v_lshl_add_u64 v[24:25], s[84:85], 0, v[22:23]
	s_waitcnt lgkmcnt(2)
	global_store_dwordx2 v[20:21], v[2:3], off
	s_waitcnt lgkmcnt(0)
	global_store_dwordx2 v[24:25], v[14:15], off
	global_store_dwordx2 v[20:21], v[4:5], off offset:8
	global_store_dwordx2 v[24:25], v[16:17], off offset:8
	global_store_dwordx2 v[20:21], v[6:7], off offset:16
	ds_read_b128 v[2:5], v35 offset:16400
	s_waitcnt lgkmcnt(0)
	global_store_dwordx2 v[24:25], v[2:3], off offset:16
	global_store_dwordx2 v[20:21], v[8:9], off offset:24
	global_store_dwordx2 v[24:25], v[4:5], off offset:24
	v_lshl_add_u64 v[2:3], s[86:87], 0, v[18:19]
	v_lshl_add_u64 v[6:7], s[86:87], 0, v[22:23]
	global_load_dwordx4 v[26:29], v[2:3], off offset:16
	global_load_dwordx4 v[14:17], v[2:3], off
	s_nop 0
	global_load_dwordx4 v[2:5], v[6:7], off offset:16
	s_nop 0
	global_load_dwordx4 v[6:9], v[6:7], off
	v_cvt_f32_i32_e32 v19, v13
	v_cvt_f32_i32_e32 v18, v12
	v_add_u32_e32 v36, -2, v36
	v_readfirstlane_b32 s0, v12
	s_cmpk_ge_u32 s0, 0x1000
	s_cbranch_scc1 .Lhyp_lean
	s_waitcnt vmcnt(2)
	v_mov_b32_e32 v20, v16
	v_mov_b32_e32 v16, v26
	s_waitcnt vmcnt(0)
	v_mov_b32_e32 v21, v8
	v_mov_b32_e32 v8, v17
	v_mov_b32_e32 v17, v2
	v_mov_b32_e32 v2, v27
	v_pk_mul_f32 v[26:27], v[18:19], s[30:31] op_sel_hi:[1,0]
	v_mov_b32_e32 v24, v14
	v_and_b32_e32 v31, 0x7fffffff, v27
	v_and_b32_e32 v30, 0x7fffffff, v26
	v_pk_mul_f32 v[18:19], v[30:31], 0.5 op_sel_hi:[1,0]
	v_cmp_gt_f32_e64 s[0:1], |v26|, 1.0
	v_fract_f32_e32 v22, v18
	v_fract_f32_e32 v23, v19
	v_pk_add_f32 v[22:23], v[22:23], v[22:23]
	v_cmp_neq_f32_e32 vcc, s9, v18
	v_cmp_gt_f32_e64 s[24:25], |v27|, 1.0
	v_mov_b32_e32 v25, v6
	v_cndmask_b32_e32 v11, 0, v22, vcc
	v_cmp_neq_f32_e32 vcc, s9, v19
	v_mov_b32_e32 v6, v15
	v_mov_b32_e32 v14, v28
	v_cndmask_b32_e32 v18, 0, v23, vcc
	v_cndmask_b32_e64 v19, |v27|, v18, s[24:25]
	v_cndmask_b32_e64 v18, |v26|, v11, s[0:1]
	v_pk_add_f32 v[22:23], v[18:19], v[18:19]
	v_mov_b32_e32 v15, v4
	v_rndne_f32_e32 v23, v23
	v_rndne_f32_e32 v22, v22
	v_mov_b32_e32 v4, v29
	v_pk_fma_f32 v[28:29], v[22:23], -0.5, v[18:19] op_sel_hi:[1,0,1]
	s_mov_b32 s0, 0xbf1f24be
	v_pk_mul_f32 v[32:33], v[28:29], v[28:29]
	v_mov_b64_e32 v[18:19], s[0:1]
	v_cvt_i32_f32_e32 v11, v23
	v_cvt_i32_f32_e32 v37, v22
	v_pk_fma_f32 v[22:23], v[32:33], s[90:91], v[18:19] op_sel_hi:[1,0,0]
	v_pk_mul_f32 v[38:39], v[28:29], v[32:33]
	v_pk_fma_f32 v[22:23], v[32:33], v[22:23], s[80:81] op_sel_hi:[1,1,0]
	s_mov_b32 s0, 0x3e642e9d
	v_pk_fma_f32 v[22:23], v[32:33], v[22:23], s[82:83] op_sel_hi:[1,1,0]
	v_xor_b32_e32 v31, v31, v27
	v_pk_mul_f32 v[22:23], v[38:39], v[22:23]
	v_xor_b32_e32 v30, v30, v26
	v_pk_fma_f32 v[28:29], v[28:29], s[92:93], v[22:23] op_sel_hi:[1,0,1]
	v_mov_b64_e32 v[22:23], s[0:1]
	v_pk_fma_f32 v[38:39], v[32:33], s[94:95], v[22:23] op_sel_hi:[1,0,0]
	s_nop 0
	v_pk_fma_f32 v[38:39], v[32:33], v[38:39], s[60:61] op_sel_hi:[1,1,0]
	s_nop 0
	v_pk_fma_f32 v[38:39], v[32:33], v[38:39], s[46:47] op_sel_hi:[1,1,0]
	s_nop 0
	v_pk_fma_f32 v[38:39], v[32:33], v[38:39], s[48:49] op_sel_hi:[1,1,0]
	s_nop 0
	v_pk_fma_f32 v[32:33], v[32:33], v[38:39], 1.0 op_sel_hi:[1,1,0]
	v_lshlrev_b32_e32 v38, 30, v11
	v_lshlrev_b32_e32 v39, 30, v37
	v_and_b32_e32 v11, 1, v11
	v_and_b32_e32 v37, 1, v37
	v_cmp_eq_u32_e32 vcc, 0, v37
	v_cmp_eq_u32_e64 s[0:1], 0, v11
	v_and_b32_e32 v38, 0x80000000, v38
	v_cndmask_b32_e32 v37, v32, v28, vcc
	v_cndmask_b32_e64 v11, v33, v29, s[0:1]
	v_and_b32_e32 v39, 0x80000000, v39
	v_xor_b32_e32 v11, v31, v11
	v_xor_b32_e32 v30, v30, v37
	v_xor_b32_e32 v11, v11, v38
	v_xor_b32_e32 v30, v30, v39
	v_cndmask_b32_e64 v29, -v29, v33, s[0:1]
	v_cndmask_b32_e64 v28, -v28, v32, vcc
	v_cmp_class_f32_e32 vcc, v26, v199
	v_cmp_class_f32_e64 s[0:1], v27, v199
	v_xor_b32_e32 v29, v38, v29
	v_xor_b32_e32 v28, v39, v28
	v_cndmask_b32_e64 v31, v217, -v11, s[0:1]
	v_cndmask_b32_e64 v30, v217, -v30, vcc
	v_cndmask_b32_e64 v29, v218, v29, s[0:1]
	v_cndmask_b32_e32 v28, v218, v28, vcc
	v_mov_b32_e32 v150, v28
	v_mov_b32_e32 v151, v29
	v_mov_b32_e32 v152, v30
	v_mov_b32_e32 v153, v31
	v_pk_mul_f32 v[26:27], v[6:7], v[30:31]
	v_or_b32_e32 v11, 1, v13
	v_pk_fma_f32 v[26:27], v[24:25], v[28:29], v[26:27] neg_lo:[0,0,1] neg_hi:[0,0,1]
	v_pk_mul_f32 v[24:25], v[24:25], v[30:31]
	s_nop 0
	v_pk_fma_f32 v[6:7], v[6:7], v[28:29], v[24:25]
	v_or_b32_e32 v24, 1, v12
	v_cvt_f32_i32_e32 v25, v11
	v_cvt_f32_i32_e32 v24, v24
	v_pk_mul_f32 v[24:25], v[24:25], s[30:31] op_sel_hi:[1,0]
	s_nop 0
	v_and_b32_e32 v29, 0x7fffffff, v25
	v_and_b32_e32 v28, 0x7fffffff, v24
	v_pk_mul_f32 v[30:31], v[28:29], 0.5 op_sel_hi:[1,0]
	v_cmp_gt_f32_e64 s[0:1], |v24|, 1.0
	v_fract_f32_e32 v32, v30
	v_fract_f32_e32 v33, v31
	v_pk_add_f32 v[32:33], v[32:33], v[32:33]
	v_cmp_neq_f32_e32 vcc, s9, v30
	v_cmp_gt_f32_e64 s[24:25], |v25|, 1.0
	v_xor_b32_e32 v28, v28, v24
	v_cndmask_b32_e32 v11, 0, v32, vcc
	v_cmp_neq_f32_e32 vcc, s9, v31
	v_xor_b32_e32 v29, v29, v25
	s_nop 0
	v_cndmask_b32_e32 v30, 0, v33, vcc
	v_cndmask_b32_e64 v31, |v25|, v30, s[24:25]
	v_cndmask_b32_e64 v30, |v24|, v11, s[0:1]
	v_pk_add_f32 v[32:33], v[30:31], v[30:31]
	s_nop 0
	v_rndne_f32_e32 v33, v33
	v_rndne_f32_e32 v32, v32
	v_pk_fma_f32 v[30:31], v[32:33], -0.5, v[30:31] op_sel_hi:[1,0,1]
	v_cvt_i32_f32_e32 v11, v33
	v_cvt_i32_f32_e32 v37, v32
	v_pk_mul_f32 v[32:33], v[30:31], v[30:31]
	s_nop 0
	v_pk_fma_f32 v[38:39], v[32:33], s[90:91], v[18:19] op_sel_hi:[1,0,0]
	v_pk_mul_f32 v[40:41], v[30:31], v[32:33]
	v_pk_fma_f32 v[38:39], v[32:33], v[38:39], s[80:81] op_sel_hi:[1,1,0]
	s_nop 0
	v_pk_fma_f32 v[38:39], v[32:33], v[38:39], s[82:83] op_sel_hi:[1,1,0]
	s_nop 0
	v_pk_mul_f32 v[38:39], v[40:41], v[38:39]
	s_nop 0
	v_pk_fma_f32 v[30:31], v[30:31], s[92:93], v[38:39] op_sel_hi:[1,0,1]
	v_pk_fma_f32 v[38:39], v[32:33], s[94:95], v[22:23] op_sel_hi:[1,0,0]
	s_nop 0
	v_pk_fma_f32 v[38:39], v[32:33], v[38:39], s[60:61] op_sel_hi:[1,1,0]
	s_nop 0
	v_pk_fma_f32 v[38:39], v[32:33], v[38:39], s[46:47] op_sel_hi:[1,1,0]
	s_nop 0
	v_pk_fma_f32 v[38:39], v[32:33], v[38:39], s[48:49] op_sel_hi:[1,1,0]
	s_nop 0
	v_pk_fma_f32 v[32:33], v[32:33], v[38:39], 1.0 op_sel_hi:[1,1,0]
	v_lshlrev_b32_e32 v39, 30, v37
	v_and_b32_e32 v37, 1, v37
	v_lshlrev_b32_e32 v38, 30, v11
	v_and_b32_e32 v11, 1, v11
	v_cmp_eq_u32_e32 vcc, 0, v37
	v_cmp_eq_u32_e64 s[0:1], 0, v11
	v_and_b32_e32 v39, 0x80000000, v39
	v_cndmask_b32_e32 v37, v32, v30, vcc
	v_cndmask_b32_e64 v11, v33, v31, s[0:1]
	v_xor_b32_e32 v28, v28, v37
	v_and_b32_e32 v38, 0x80000000, v38
	v_xor_b32_e32 v11, v29, v11
	v_xor_b32_e32 v37, v28, v39
	v_cndmask_b32_e64 v28, -v31, v33, s[0:1]
	v_cndmask_b32_e64 v29, -v30, v32, vcc
	v_xor_b32_e32 v11, v11, v38
	v_xor_b32_e32 v28, v38, v28
	v_xor_b32_e32 v30, v39, v29
	v_cmp_class_f32_e32 vcc, v24, v199
	v_cmp_class_f32_e64 s[0:1], v25, v199
	s_nop 1
	v_cndmask_b32_e64 v29, v218, v28, s[0:1]
	v_cndmask_b32_e32 v28, v218, v30, vcc
	v_cndmask_b32_e64 v31, v217, -v11, s[0:1]
	v_cndmask_b32_e64 v30, v217, -v37, vcc
	v_mov_b32_e32 v154, v28
	v_mov_b32_e32 v155, v29
	v_mov_b32_e32 v156, v30
	v_mov_b32_e32 v157, v31
	v_pk_mul_f32 v[24:25], v[8:9], v[30:31]
	v_or_b32_e32 v11, 2, v13
	v_pk_fma_f32 v[24:25], v[20:21], v[28:29], v[24:25] neg_lo:[0,0,1] neg_hi:[0,0,1]
	v_pk_mul_f32 v[20:21], v[20:21], v[30:31]
	s_nop 0
	v_pk_fma_f32 v[8:9], v[8:9], v[28:29], v[20:21]
	v_or_b32_e32 v20, 2, v12
	v_cvt_f32_i32_e32 v21, v11
	v_cvt_f32_i32_e32 v20, v20
	v_pk_mul_f32 v[20:21], v[20:21], s[30:31] op_sel_hi:[1,0]
	s_nop 0
	v_and_b32_e32 v29, 0x7fffffff, v21
	v_and_b32_e32 v28, 0x7fffffff, v20
	v_pk_mul_f32 v[30:31], v[28:29], 0.5 op_sel_hi:[1,0]
	v_cmp_gt_f32_e64 s[0:1], |v20|, 1.0
	v_fract_f32_e32 v32, v30
	v_fract_f32_e32 v33, v31
	v_pk_add_f32 v[32:33], v[32:33], v[32:33]
	v_cmp_neq_f32_e32 vcc, s9, v30
	v_cmp_gt_f32_e64 s[24:25], |v21|, 1.0
	v_xor_b32_e32 v29, v29, v21
	v_cndmask_b32_e32 v11, 0, v32, vcc
	v_cmp_neq_f32_e32 vcc, s9, v31
	v_xor_b32_e32 v28, v28, v20
	s_nop 0
	v_cndmask_b32_e32 v30, 0, v33, vcc
	v_cndmask_b32_e64 v31, |v21|, v30, s[24:25]
	v_cndmask_b32_e64 v30, |v20|, v11, s[0:1]
	v_pk_add_f32 v[32:33], v[30:31], v[30:31]
	s_nop 0
	v_rndne_f32_e32 v33, v33
	v_rndne_f32_e32 v32, v32
	v_pk_fma_f32 v[30:31], v[32:33], -0.5, v[30:31] op_sel_hi:[1,0,1]
	v_cvt_i32_f32_e32 v11, v33
	v_cvt_i32_f32_e32 v37, v32
	v_pk_mul_f32 v[32:33], v[30:31], v[30:31]
	s_nop 0
	v_pk_fma_f32 v[38:39], v[32:33], s[90:91], v[18:19] op_sel_hi:[1,0,0]
	v_pk_mul_f32 v[40:41], v[30:31], v[32:33]
	v_pk_fma_f32 v[38:39], v[32:33], v[38:39], s[80:81] op_sel_hi:[1,1,0]
	s_nop 0
	v_pk_fma_f32 v[38:39], v[32:33], v[38:39], s[82:83] op_sel_hi:[1,1,0]
	s_nop 0
	v_pk_mul_f32 v[38:39], v[40:41], v[38:39]
	s_nop 0
	v_pk_fma_f32 v[30:31], v[30:31], s[92:93], v[38:39] op_sel_hi:[1,0,1]
	v_pk_fma_f32 v[38:39], v[32:33], s[94:95], v[22:23] op_sel_hi:[1,0,0]
	s_nop 0
	v_pk_fma_f32 v[38:39], v[32:33], v[38:39], s[60:61] op_sel_hi:[1,1,0]
	s_nop 0
	v_pk_fma_f32 v[38:39], v[32:33], v[38:39], s[46:47] op_sel_hi:[1,1,0]
	s_nop 0
	v_pk_fma_f32 v[38:39], v[32:33], v[38:39], s[48:49] op_sel_hi:[1,1,0]
	s_nop 0
	v_pk_fma_f32 v[32:33], v[32:33], v[38:39], 1.0 op_sel_hi:[1,1,0]
	v_lshlrev_b32_e32 v38, 30, v11
	v_lshlrev_b32_e32 v39, 30, v37
	v_and_b32_e32 v11, 1, v11
	v_and_b32_e32 v37, 1, v37
	v_cmp_eq_u32_e32 vcc, 0, v37
	v_cmp_eq_u32_e64 s[0:1], 0, v11
	v_and_b32_e32 v38, 0x80000000, v38
	v_cndmask_b32_e32 v37, v32, v30, vcc
	v_cndmask_b32_e64 v11, v33, v31, s[0:1]
	v_and_b32_e32 v39, 0x80000000, v39
	v_xor_b32_e32 v11, v29, v11
	v_xor_b32_e32 v28, v28, v37
	v_cndmask_b32_e64 v29, -v31, v33, s[0:1]
	v_xor_b32_e32 v11, v11, v38
	v_xor_b32_e32 v28, v28, v39
	v_cndmask_b32_e64 v30, -v30, v32, vcc
	v_xor_b32_e32 v29, v38, v29
	v_cmp_class_f32_e32 vcc, v20, v199
	v_cmp_class_f32_e64 s[0:1], v21, v199
	v_xor_b32_e32 v30, v39, v30
	v_cndmask_b32_e64 v28, v217, -v28, vcc
	v_cndmask_b32_e64 v21, v218, v29, s[0:1]
	v_cndmask_b32_e64 v29, v217, -v11, s[0:1]
	v_cndmask_b32_e32 v20, v218, v30, vcc
	v_mov_b32_e32 v158, v20
	v_mov_b32_e32 v159, v21
	v_mov_b32_e32 v160, v28
	v_mov_b32_e32 v161, v29
	v_pk_mul_f32 v[30:31], v[2:3], v[28:29]
	v_or_b32_e32 v11, 3, v13
	v_pk_fma_f32 v[30:31], v[16:17], v[20:21], v[30:31] neg_lo:[0,0,1] neg_hi:[0,0,1]
	v_pk_mul_f32 v[16:17], v[16:17], v[28:29]
	v_add_u32_e32 v13, 0x1000, v13
	v_pk_fma_f32 v[2:3], v[2:3], v[20:21], v[16:17]
	v_or_b32_e32 v16, 3, v12
	v_cvt_f32_i32_e32 v17, v11
	v_cvt_f32_i32_e32 v16, v16
	v_add_u32_e32 v12, 0x1000, v12
	v_pk_mul_f32 v[16:17], v[16:17], s[30:31] op_sel_hi:[1,0]
	s_nop 0
	v_and_b32_e32 v21, 0x7fffffff, v17
	v_and_b32_e32 v20, 0x7fffffff, v16
	v_pk_mul_f32 v[28:29], v[20:21], 0.5 op_sel_hi:[1,0]
	v_cmp_gt_f32_e64 s[0:1], |v16|, 1.0
	v_fract_f32_e32 v32, v28
	v_fract_f32_e32 v33, v29
	v_pk_add_f32 v[32:33], v[32:33], v[32:33]
	v_cmp_neq_f32_e32 vcc, s9, v28
	v_cmp_gt_f32_e64 s[24:25], |v17|, 1.0
	v_xor_b32_e32 v21, v21, v17
	v_cndmask_b32_e32 v11, 0, v32, vcc
	v_cmp_neq_f32_e32 vcc, s9, v29
	v_xor_b32_e32 v20, v20, v16
	s_nop 0
	v_cndmask_b32_e32 v28, 0, v33, vcc
	v_cndmask_b32_e64 v29, |v17|, v28, s[24:25]
	v_cndmask_b32_e64 v28, |v16|, v11, s[0:1]
	v_pk_add_f32 v[32:33], v[28:29], v[28:29]
	s_nop 0
	v_rndne_f32_e32 v33, v33
	v_rndne_f32_e32 v32, v32
	v_pk_fma_f32 v[28:29], v[32:33], -0.5, v[28:29] op_sel_hi:[1,0,1]
	v_cvt_i32_f32_e32 v11, v33
	v_cvt_i32_f32_e32 v37, v32
	v_pk_mul_f32 v[32:33], v[28:29], v[28:29]
	s_nop 0
	v_pk_fma_f32 v[18:19], v[32:33], s[90:91], v[18:19] op_sel_hi:[1,0,0]
	v_pk_fma_f32 v[22:23], v[32:33], s[94:95], v[22:23] op_sel_hi:[1,0,0]
	v_pk_fma_f32 v[18:19], v[32:33], v[18:19], s[80:81] op_sel_hi:[1,1,0]
	v_pk_fma_f32 v[22:23], v[32:33], v[22:23], s[60:61] op_sel_hi:[1,1,0]
	v_pk_fma_f32 v[18:19], v[32:33], v[18:19], s[82:83] op_sel_hi:[1,1,0]
	v_pk_mul_f32 v[38:39], v[28:29], v[32:33]
	v_pk_fma_f32 v[22:23], v[32:33], v[22:23], s[46:47] op_sel_hi:[1,1,0]
	v_pk_mul_f32 v[18:19], v[38:39], v[18:19]
	v_pk_fma_f32 v[22:23], v[32:33], v[22:23], s[48:49] op_sel_hi:[1,1,0]
	v_pk_fma_f32 v[18:19], v[28:29], s[92:93], v[18:19] op_sel_hi:[1,0,1]
	v_pk_fma_f32 v[22:23], v[32:33], v[22:23], 1.0 op_sel_hi:[1,1,0]
	v_lshlrev_b32_e32 v28, 30, v11
	v_and_b32_e32 v11, 1, v11
	v_and_b32_e32 v32, 1, v37
	v_cmp_eq_u32_e32 vcc, 0, v32
	v_cmp_eq_u32_e64 s[0:1], 0, v11
	v_lshlrev_b32_e32 v29, 30, v37
	v_cndmask_b32_e32 v32, v22, v18, vcc
	v_cndmask_b32_e64 v11, v23, v19, s[0:1]
	v_and_b32_e32 v28, 0x80000000, v28
	v_and_b32_e32 v29, 0x80000000, v29
	v_xor_b32_e32 v11, v21, v11
	v_xor_b32_e32 v20, v20, v32
	v_cndmask_b32_e64 v19, -v19, v23, s[0:1]
	v_cndmask_b32_e64 v18, -v18, v22, vcc
	v_xor_b32_e32 v11, v11, v28
	v_xor_b32_e32 v20, v20, v29
	v_xor_b32_e32 v19, v28, v19
	v_xor_b32_e32 v18, v29, v18
	v_cmp_class_f32_e32 vcc, v16, v199
	v_cmp_class_f32_e64 s[0:1], v17, v199
	s_nop 0
	v_cndmask_b32_e32 v16, v218, v18, vcc
	v_cndmask_b32_e64 v17, v218, v19, s[0:1]
	v_cndmask_b32_e64 v19, v217, -v11, s[0:1]
	v_cndmask_b32_e64 v18, v217, -v20, vcc
	v_mov_b32_e32 v162, v16
	v_mov_b32_e32 v163, v17
	v_mov_b32_e32 v164, v18
	v_mov_b32_e32 v165, v19
	v_pk_mul_f32 v[20:21], v[4:5], v[18:19]
	v_cmp_eq_u32_e32 vcc, 0, v36
	v_pk_fma_f32 v[20:21], v[14:15], v[16:17], v[20:21] neg_lo:[0,0,1] neg_hi:[0,0,1]
	v_pk_mul_f32 v[14:15], v[14:15], v[18:19]
	s_or_b64 s[26:27], vcc, s[26:27]
	v_pk_fma_f32 v[4:5], v[4:5], v[16:17], v[14:15]
	v_mov_b32_e32 v15, v6
	v_mov_b32_e32 v17, v8
	v_mov_b32_e32 v6, v27
	v_mov_b32_e32 v8, v25
	v_mov_b32_e32 v14, v26
	v_mov_b32_e32 v16, v24
	ds_write_b128 v35, v[6:9] offset:16384
	v_mov_b32_e32 v6, v30
	v_mov_b32_e32 v7, v2
	v_mov_b32_e32 v8, v20
	v_mov_b32_e32 v9, v4
	v_mov_b32_e32 v2, v31
	v_mov_b32_e32 v4, v21
	ds_write_b128 v35, v[14:17]
	ds_write_b128 v35, v[6:9] offset:16
	ds_write_b128 v35, v[2:5] offset:16400
	v_add_u32_e32 v35, 0x8000, v35
	s_andn2_b64 exec, exec, s[26:27]
	s_cbranch_execnz .LBB0_1038
	s_branch .Lhyp_exit
.Lhyp_lean:
	s_waitcnt vmcnt(0)
	v_mov_b32_e32 v20, v16
	v_mov_b32_e32 v16, v26
	v_mov_b32_e32 v21, v8
	v_mov_b32_e32 v8, v17
	v_mov_b32_e32 v17, v2
	v_mov_b32_e32 v2, v27
	v_mov_b32_e32 v24, v14
	v_mov_b32_e32 v25, v6
	v_mov_b32_e32 v6, v15
	v_mov_b32_e32 v14, v28
	v_mov_b32_e32 v15, v4
	v_mov_b32_e32 v4, v29
	s_mov_b32 s0, 0x3f3504f3
	v_pk_add_f32 v[22:23], v[150:151], v[152:153]
	v_pk_add_f32 v[152:153], v[152:153], v[150:151] neg_lo:[0,1] neg_hi:[0,1]
	v_pk_add_f32 v[18:19], v[154:155], v[156:157]
	v_pk_add_f32 v[156:157], v[156:157], v[154:155] neg_lo:[0,1] neg_hi:[0,1]
	v_pk_add_f32 v[28:29], v[158:159], v[160:161]
	v_pk_add_f32 v[160:161], v[160:161], v[158:159] neg_lo:[0,1] neg_hi:[0,1]
	v_pk_add_f32 v[32:33], v[162:163], v[164:165]
	v_pk_add_f32 v[164:165], v[164:165], v[162:163] neg_lo:[0,1] neg_hi:[0,1]
	s_nop 0
	v_pk_mul_f32 v[150:151], v[22:23], s[0:1] op_sel_hi:[1,0]
	v_pk_mul_f32 v[152:153], v[152:153], s[0:1] op_sel_hi:[1,0]
	v_pk_mul_f32 v[154:155], v[18:19], s[0:1] op_sel_hi:[1,0]
	v_pk_mul_f32 v[156:157], v[156:157], s[0:1] op_sel_hi:[1,0]
	v_pk_mul_f32 v[158:159], v[28:29], s[0:1] op_sel_hi:[1,0]
	v_pk_mul_f32 v[160:161], v[160:161], s[0:1] op_sel_hi:[1,0]
	v_pk_mul_f32 v[162:163], v[32:33], s[0:1] op_sel_hi:[1,0]
	v_pk_mul_f32 v[164:165], v[164:165], s[0:1] op_sel_hi:[1,0]
	s_nop 0
	v_pk_mul_f32 v[26:27], v[6:7], v[152:153]
	s_nop 0
	v_pk_fma_f32 v[26:27], v[24:25], v[150:151], v[26:27] neg_lo:[0,0,1] neg_hi:[0,0,1]
	v_pk_mul_f32 v[24:25], v[24:25], v[152:153]
	s_nop 0
	v_pk_fma_f32 v[6:7], v[6:7], v[150:151], v[24:25]
	v_pk_mul_f32 v[24:25], v[8:9], v[156:157]
	s_nop 0
	v_pk_fma_f32 v[24:25], v[20:21], v[154:155], v[24:25] neg_lo:[0,0,1] neg_hi:[0,0,1]
	v_pk_mul_f32 v[20:21], v[20:21], v[156:157]
	s_nop 0
	v_pk_fma_f32 v[8:9], v[8:9], v[154:155], v[20:21]
	v_pk_mul_f32 v[30:31], v[2:3], v[160:161]
	s_nop 0
	v_pk_fma_f32 v[30:31], v[16:17], v[158:159], v[30:31] neg_lo:[0,0,1] neg_hi:[0,0,1]
	v_pk_mul_f32 v[16:17], v[16:17], v[160:161]
	s_nop 0
	v_pk_fma_f32 v[2:3], v[2:3], v[158:159], v[16:17]
	v_pk_mul_f32 v[20:21], v[4:5], v[164:165]
	s_nop 0
	v_pk_fma_f32 v[20:21], v[14:15], v[162:163], v[20:21] neg_lo:[0,0,1] neg_hi:[0,0,1]
	v_pk_mul_f32 v[14:15], v[14:15], v[164:165]
	s_nop 0
	v_pk_fma_f32 v[4:5], v[4:5], v[162:163], v[14:15]
	v_add_u32_e32 v13, 0x1000, v13
	v_add_u32_e32 v12, 0x1000, v12
	v_cmp_eq_u32_e32 vcc, 0, v36
	s_or_b64 s[26:27], vcc, s[26:27]
	v_mov_b32_e32 v15, v6
	v_mov_b32_e32 v17, v8
	v_mov_b32_e32 v6, v27
	v_mov_b32_e32 v8, v25
	v_mov_b32_e32 v14, v26
	v_mov_b32_e32 v16, v24
	ds_write_b128 v35, v[6:9] offset:16384
	v_mov_b32_e32 v6, v30
	v_mov_b32_e32 v7, v2
	v_mov_b32_e32 v8, v20
	v_mov_b32_e32 v9, v4
	v_mov_b32_e32 v2, v31
	v_mov_b32_e32 v4, v21
	ds_write_b128 v35, v[14:17]
	ds_write_b128 v35, v[6:9] offset:16
	ds_write_b128 v35, v[2:5] offset:16400
	v_add_u32_e32 v35, 0x8000, v35
	s_andn2_b64 exec, exec, s[26:27]
	s_cbranch_execnz .LBB0_1038
.Lhyp_exit:
	s_or_b64 exec, exec, s[26:27]
	v_cmp_ne_u32_e32 vcc, v0, v34
	v_lshl_add_u32 v10, v34, 11, v10
	s_orn2_b64 s[0:1], vcc, exec
